# workgroups owning one unit fewer in GEMM phases 1/8/11 enter the phase 10-12 us late (their epilogue store bursts fall between the others'); EpiQK1 rope ring in 3 fixed buffers, stores after the last
# speedup vs baseline: 1.0171x; 1.0023x over previous
.LBB0_22:
	s_cmp_eq_u32 s66, 11
	s_cbranch_scc0 .Lstg_n0
	s_cmp_ge_u32 s99, 128
	s_cbranch_scc0 .Lstg_end
	s_movk_i32 s98, 1200
	s_branch .Lstg_go
.Lstg_n0:
	s_cmp_eq_u32 s66, 8
	s_cbranch_scc0 .Lstg_n1
	s_cmp_ge_u32 s99, 128
	s_cbranch_scc0 .Lstg_end
	s_movk_i32 s98, 1000
	s_branch .Lstg_go
.Lstg_n1:
	s_cmp_eq_u32 s66, 1
	s_cbranch_scc0 .Lstg_n2
	s_cmp_ge_u32 s99, 192
	s_cbranch_scc0 .Lstg_end
	s_movk_i32 s98, 1200
	s_branch .Lstg_go

.Lstg_go:
	s_memrealtime vcc
	s_waitcnt lgkmcnt(0)
	s_add_u32 s98, vcc_lo, s98
.Lstg_spin:
	s_sleep 4
	s_memrealtime vcc
	s_waitcnt lgkmcnt(0)
	s_sub_u32 vcc_lo, vcc_lo, s98
	s_cmp_lt_i32 vcc_lo, 0
	s_cbranch_scc1 .Lstg_spin

.LBB0_201:
	s_and_b64 vcc, exec, s[0:1]
	s_cbranch_vccz .LBB0_203
	s_lshl_b32 s0, s7, 2
	s_add_i32 s0, s68, s0
	v_lshl_add_u32 v183, v155, 2, s0
	ds_read2_b32 v[244:245], v183 offset1:16
	ds_read2_b32 v[246:247], v183 offset0:32 offset1:48
	ds_read2_b32 v[248:249], v183 offset0:128 offset1:144
	ds_read2_b32 v[250:251], v183 offset0:160 offset1:176
	s_lshl_b32 s9, s72, 9
	s_cmp_lt_i32 s72, 4
	s_cselect_b32 s1, s74, s96
	s_cselect_b32 s0, s83, s86
	s_cselect_b32 s8, 11, 9
	s_mov_b32 s24, 0x9200000
	s_cselect_b32 s24, 0x7200000, s24
	s_cselect_b32 s9, s9, 0
	s_mov_b32 s42, 0x3e38aa3b
	s_cselect_b32 s42, s42, 1.0
	v_readlane_b32 s2, v255, 42
	s_lshl_b32 s2, s2, 1
	s_add_u32 s9, s9, s2
	s_add_u32 s24, s24, s9
	v_readlane_b32 s2, v254, 37
	v_readlane_b32 s3, v254, 38
	s_add_u32 s44, s2, s24
	s_addc_u32 s45, s3, 0
	s_mov_b32 s9, s42
	s_add_u32 s42, s2, 0x1f00000
	s_addc_u32 s43, s3, 0
	s_lshl_b32 s24, 16, s8
	v_lshlrev_b32_e32 v177, 2, v154
	global_load_dwordx4 v[128:131], v177, s[0:1]
	global_load_dwordx4 v[132:135], v177, s[0:1] offset:16
	global_load_dwordx4 v[136:139], v177, s[0:1] offset:128
	global_load_dwordx4 v[140:143], v177, s[0:1] offset:144
	v_lshl_add_u32 v176, s76, 8, v178
	v_and_b32_e32 v174, 0x7ff, v176
	v_lshl_add_u32 v177, v174, 8, v177
	v_lshlrev_b32_e32 v176, s8, v176
	v_lshl_add_u32 v176, v154, 1, v176
	global_load_dwordx4 v[188:191], v177, s[42:43] offset:16
	global_load_dwordx4 v[196:199], v177, s[42:43] offset:144
	global_load_dwordx4 v[184:187], v177, s[42:43]
	global_load_dwordx4 v[192:195], v177, s[42:43] offset:128
	s_add_u32 s42, s42, 0x1000
	s_addc_u32 s43, s43, 0
	global_load_dwordx4 v[204:207], v177, s[42:43] offset:16
	global_load_dwordx4 v[212:215], v177, s[42:43] offset:144
	global_load_dwordx4 v[200:203], v177, s[42:43]
	global_load_dwordx4 v[208:211], v177, s[42:43] offset:128
	s_add_u32 s42, s42, 0x1000
	s_addc_u32 s43, s43, 0
	global_load_dwordx4 v[220:223], v177, s[42:43] offset:16
	global_load_dwordx4 v[168:171], v177, s[42:43] offset:144
	global_load_dwordx4 v[216:219], v177, s[42:43]
	global_load_dwordx4 v[164:167], v177, s[42:43] offset:128
	s_add_u32 s42, s42, 0x1000
	s_addc_u32 s43, s43, 0
	s_waitcnt lgkmcnt(0)
	v_cmp_lt_i32_e32 vcc, v230, v228
	v_pk_mul_f32 v[124:125], v[124:125], v[244:245] op_sel_hi:[1,0]
	v_pk_mul_f32 v[126:127], v[126:127], v[244:245] op_sel_hi:[1,0]
	v_pk_mul_f32 v[120:121], v[120:121], v[244:245] op_sel_hi:[1,0]
	v_pk_mul_f32 v[122:123], v[122:123], v[244:245] op_sel_hi:[1,0]
	v_pk_mul_f32 v[92:93], v[92:93], v[244:245] op_sel_hi:[1,0]
	v_pk_mul_f32 v[94:95], v[94:95], v[244:245] op_sel_hi:[1,0]
	v_pk_mul_f32 v[88:89], v[88:89], v[244:245] op_sel_hi:[1,0]
	v_pk_mul_f32 v[90:91], v[90:91], v[244:245] op_sel_hi:[1,0]
	v_pk_mul_f32 v[172:173], v[124:125], v[124:125]
	v_pk_fma_f32 v[172:173], v[126:127], v[126:127], v[172:173]
	v_pk_fma_f32 v[172:173], v[120:121], v[120:121], v[172:173]
	v_pk_fma_f32 v[172:173], v[122:123], v[122:123], v[172:173]
	v_pk_fma_f32 v[172:173], v[92:93], v[92:93], v[172:173]
	v_pk_fma_f32 v[172:173], v[94:95], v[94:95], v[172:173]
	v_pk_fma_f32 v[172:173], v[88:89], v[88:89], v[172:173]
	v_pk_fma_f32 v[172:173], v[90:91], v[90:91], v[172:173]
	v_cndmask_b32_e32 v183, v226, v230, vcc
	v_cmp_lt_i32_e32 vcc, v229, v228
	v_lshlrev_b32_e32 v183, 2, v183
	v_add_f32_e32 v232, v172, v173
	v_pk_mul_f32 v[116:117], v[116:117], v[244:245] op_sel:[0,1] op_sel_hi:[1,1]
	v_pk_mul_f32 v[118:119], v[118:119], v[244:245] op_sel:[0,1] op_sel_hi:[1,1]
	v_pk_mul_f32 v[112:113], v[112:113], v[244:245] op_sel:[0,1] op_sel_hi:[1,1]
	v_pk_mul_f32 v[114:115], v[114:115], v[244:245] op_sel:[0,1] op_sel_hi:[1,1]
	v_pk_mul_f32 v[84:85], v[84:85], v[244:245] op_sel:[0,1] op_sel_hi:[1,1]
	v_pk_mul_f32 v[86:87], v[86:87], v[244:245] op_sel:[0,1] op_sel_hi:[1,1]
	v_pk_mul_f32 v[80:81], v[80:81], v[244:245] op_sel:[0,1] op_sel_hi:[1,1]
	v_pk_mul_f32 v[82:83], v[82:83], v[244:245] op_sel:[0,1] op_sel_hi:[1,1]
	v_pk_mul_f32 v[172:173], v[116:117], v[116:117]
	v_pk_fma_f32 v[172:173], v[118:119], v[118:119], v[172:173]
	v_pk_fma_f32 v[172:173], v[112:113], v[112:113], v[172:173]
	v_pk_fma_f32 v[172:173], v[114:115], v[114:115], v[172:173]
	v_pk_fma_f32 v[172:173], v[84:85], v[84:85], v[172:173]
	v_pk_fma_f32 v[172:173], v[86:87], v[86:87], v[172:173]
	v_pk_fma_f32 v[172:173], v[80:81], v[80:81], v[172:173]
	v_pk_fma_f32 v[172:173], v[82:83], v[82:83], v[172:173]
	v_cndmask_b32_e32 v174, v226, v229, vcc
	v_lshlrev_b32_e32 v174, 2, v174
	v_add_f32_e32 v233, v172, v173
	v_pk_mul_f32 v[108:109], v[108:109], v[246:247] op_sel_hi:[1,0]
	v_pk_mul_f32 v[110:111], v[110:111], v[246:247] op_sel_hi:[1,0]
	v_pk_mul_f32 v[104:105], v[104:105], v[246:247] op_sel_hi:[1,0]
	v_pk_mul_f32 v[106:107], v[106:107], v[246:247] op_sel_hi:[1,0]
	v_pk_mul_f32 v[76:77], v[76:77], v[246:247] op_sel_hi:[1,0]
	v_pk_mul_f32 v[78:79], v[78:79], v[246:247] op_sel_hi:[1,0]
	v_pk_mul_f32 v[72:73], v[72:73], v[246:247] op_sel_hi:[1,0]
	v_pk_mul_f32 v[74:75], v[74:75], v[246:247] op_sel_hi:[1,0]
	v_pk_mul_f32 v[172:173], v[108:109], v[108:109]
	v_pk_fma_f32 v[172:173], v[110:111], v[110:111], v[172:173]
	v_pk_fma_f32 v[172:173], v[104:105], v[104:105], v[172:173]
	v_pk_fma_f32 v[172:173], v[106:107], v[106:107], v[172:173]
	v_pk_fma_f32 v[172:173], v[76:77], v[76:77], v[172:173]
	v_pk_fma_f32 v[172:173], v[78:79], v[78:79], v[172:173]
	v_pk_fma_f32 v[172:173], v[72:73], v[72:73], v[172:173]
	v_pk_fma_f32 v[172:173], v[74:75], v[74:75], v[172:173]
	v_add_f32_e32 v234, v172, v173
	v_pk_mul_f32 v[100:101], v[100:101], v[246:247] op_sel:[0,1] op_sel_hi:[1,1]
	v_pk_mul_f32 v[102:103], v[102:103], v[246:247] op_sel:[0,1] op_sel_hi:[1,1]
	v_pk_mul_f32 v[96:97], v[96:97], v[246:247] op_sel:[0,1] op_sel_hi:[1,1]
	v_pk_mul_f32 v[98:99], v[98:99], v[246:247] op_sel:[0,1] op_sel_hi:[1,1]
	v_pk_mul_f32 v[68:69], v[68:69], v[246:247] op_sel:[0,1] op_sel_hi:[1,1]
	v_pk_mul_f32 v[70:71], v[70:71], v[246:247] op_sel:[0,1] op_sel_hi:[1,1]
	v_pk_mul_f32 v[64:65], v[64:65], v[246:247] op_sel:[0,1] op_sel_hi:[1,1]
	v_pk_mul_f32 v[66:67], v[66:67], v[246:247] op_sel:[0,1] op_sel_hi:[1,1]
	v_pk_mul_f32 v[172:173], v[100:101], v[100:101]
	v_pk_fma_f32 v[172:173], v[102:103], v[102:103], v[172:173]
	v_pk_fma_f32 v[172:173], v[96:97], v[96:97], v[172:173]
	v_pk_fma_f32 v[172:173], v[98:99], v[98:99], v[172:173]
	v_pk_fma_f32 v[172:173], v[68:69], v[68:69], v[172:173]
	v_pk_fma_f32 v[172:173], v[70:71], v[70:71], v[172:173]
	v_pk_fma_f32 v[172:173], v[64:65], v[64:65], v[172:173]
	v_pk_fma_f32 v[172:173], v[66:67], v[66:67], v[172:173]
	v_add_f32_e32 v235, v172, v173
	v_pk_mul_f32 v[60:61], v[60:61], v[248:249] op_sel_hi:[1,0]
	v_pk_mul_f32 v[62:63], v[62:63], v[248:249] op_sel_hi:[1,0]
	v_pk_mul_f32 v[56:57], v[56:57], v[248:249] op_sel_hi:[1,0]
	v_pk_mul_f32 v[58:59], v[58:59], v[248:249] op_sel_hi:[1,0]
	v_pk_mul_f32 v[28:29], v[28:29], v[248:249] op_sel_hi:[1,0]
	v_pk_mul_f32 v[30:31], v[30:31], v[248:249] op_sel_hi:[1,0]
	v_pk_mul_f32 v[24:25], v[24:25], v[248:249] op_sel_hi:[1,0]
	v_pk_mul_f32 v[26:27], v[26:27], v[248:249] op_sel_hi:[1,0]
	v_pk_mul_f32 v[172:173], v[60:61], v[60:61]
	v_pk_fma_f32 v[172:173], v[62:63], v[62:63], v[172:173]
	v_pk_fma_f32 v[172:173], v[56:57], v[56:57], v[172:173]
	v_pk_fma_f32 v[172:173], v[58:59], v[58:59], v[172:173]
	v_pk_fma_f32 v[172:173], v[28:29], v[28:29], v[172:173]
	v_pk_fma_f32 v[172:173], v[30:31], v[30:31], v[172:173]
	v_pk_fma_f32 v[172:173], v[24:25], v[24:25], v[172:173]
	v_pk_fma_f32 v[172:173], v[26:27], v[26:27], v[172:173]
	v_add_f32_e32 v236, v172, v173
	v_pk_mul_f32 v[52:53], v[52:53], v[248:249] op_sel:[0,1] op_sel_hi:[1,1]
	v_pk_mul_f32 v[54:55], v[54:55], v[248:249] op_sel:[0,1] op_sel_hi:[1,1]
	v_pk_mul_f32 v[48:49], v[48:49], v[248:249] op_sel:[0,1] op_sel_hi:[1,1]
	v_pk_mul_f32 v[50:51], v[50:51], v[248:249] op_sel:[0,1] op_sel_hi:[1,1]
	v_pk_mul_f32 v[20:21], v[20:21], v[248:249] op_sel:[0,1] op_sel_hi:[1,1]
	v_pk_mul_f32 v[22:23], v[22:23], v[248:249] op_sel:[0,1] op_sel_hi:[1,1]
	v_pk_mul_f32 v[16:17], v[16:17], v[248:249] op_sel:[0,1] op_sel_hi:[1,1]
	v_pk_mul_f32 v[18:19], v[18:19], v[248:249] op_sel:[0,1] op_sel_hi:[1,1]
	v_pk_mul_f32 v[172:173], v[52:53], v[52:53]
	v_pk_fma_f32 v[172:173], v[54:55], v[54:55], v[172:173]
	v_pk_fma_f32 v[172:173], v[48:49], v[48:49], v[172:173]
	v_pk_fma_f32 v[172:173], v[50:51], v[50:51], v[172:173]
	v_pk_fma_f32 v[172:173], v[20:21], v[20:21], v[172:173]
	v_pk_fma_f32 v[172:173], v[22:23], v[22:23], v[172:173]
	v_pk_fma_f32 v[172:173], v[16:17], v[16:17], v[172:173]
	v_pk_fma_f32 v[172:173], v[18:19], v[18:19], v[172:173]
	v_add_f32_e32 v237, v172, v173
	v_pk_mul_f32 v[44:45], v[44:45], v[250:251] op_sel_hi:[1,0]
	v_pk_mul_f32 v[46:47], v[46:47], v[250:251] op_sel_hi:[1,0]
	v_pk_mul_f32 v[40:41], v[40:41], v[250:251] op_sel_hi:[1,0]
	v_pk_mul_f32 v[42:43], v[42:43], v[250:251] op_sel_hi:[1,0]
	v_pk_mul_f32 v[12:13], v[12:13], v[250:251] op_sel_hi:[1,0]
	v_pk_mul_f32 v[14:15], v[14:15], v[250:251] op_sel_hi:[1,0]
	v_pk_mul_f32 v[8:9], v[8:9], v[250:251] op_sel_hi:[1,0]
	v_pk_mul_f32 v[10:11], v[10:11], v[250:251] op_sel_hi:[1,0]
	v_pk_mul_f32 v[172:173], v[44:45], v[44:45]
	v_pk_fma_f32 v[172:173], v[46:47], v[46:47], v[172:173]
	v_pk_fma_f32 v[172:173], v[40:41], v[40:41], v[172:173]
	v_pk_fma_f32 v[172:173], v[42:43], v[42:43], v[172:173]
	v_pk_fma_f32 v[172:173], v[12:13], v[12:13], v[172:173]
	v_pk_fma_f32 v[172:173], v[14:15], v[14:15], v[172:173]
	v_pk_fma_f32 v[172:173], v[8:9], v[8:9], v[172:173]
	v_pk_fma_f32 v[172:173], v[10:11], v[10:11], v[172:173]
	v_add_f32_e32 v240, v172, v173
	v_pk_mul_f32 v[36:37], v[36:37], v[250:251] op_sel:[0,1] op_sel_hi:[1,1]
	v_pk_mul_f32 v[38:39], v[38:39], v[250:251] op_sel:[0,1] op_sel_hi:[1,1]
	v_pk_mul_f32 v[32:33], v[32:33], v[250:251] op_sel:[0,1] op_sel_hi:[1,1]
	v_pk_mul_f32 v[34:35], v[34:35], v[250:251] op_sel:[0,1] op_sel_hi:[1,1]
	v_pk_mul_f32 v[4:5], v[4:5], v[250:251] op_sel:[0,1] op_sel_hi:[1,1]
	v_pk_mul_f32 v[6:7], v[6:7], v[250:251] op_sel:[0,1] op_sel_hi:[1,1]
	v_pk_mul_f32 v[0:1], v[0:1], v[250:251] op_sel:[0,1] op_sel_hi:[1,1]
	v_pk_mul_f32 v[2:3], v[2:3], v[250:251] op_sel:[0,1] op_sel_hi:[1,1]
	v_pk_mul_f32 v[172:173], v[36:37], v[36:37]
	v_pk_fma_f32 v[172:173], v[38:39], v[38:39], v[172:173]
	v_pk_fma_f32 v[172:173], v[32:33], v[32:33], v[172:173]
	v_pk_fma_f32 v[172:173], v[34:35], v[34:35], v[172:173]
	v_pk_fma_f32 v[172:173], v[4:5], v[4:5], v[172:173]
	v_pk_fma_f32 v[172:173], v[6:7], v[6:7], v[172:173]
	v_pk_fma_f32 v[172:173], v[0:1], v[0:1], v[172:173]
	v_pk_fma_f32 v[172:173], v[2:3], v[2:3], v[172:173]
	v_add_f32_e32 v241, v172, v173
	ds_bpermute_b32 v244, v183, v232
	ds_bpermute_b32 v245, v183, v233
	ds_bpermute_b32 v246, v183, v234
	ds_bpermute_b32 v247, v183, v235
	ds_bpermute_b32 v248, v183, v236
	ds_bpermute_b32 v249, v183, v237
	ds_bpermute_b32 v250, v183, v240
	ds_bpermute_b32 v251, v183, v241
	s_waitcnt lgkmcnt(6)
	v_pk_add_f32 v[232:233], v[232:233], v[244:245]
	s_waitcnt lgkmcnt(4)
	v_pk_add_f32 v[234:235], v[234:235], v[246:247]
	s_waitcnt lgkmcnt(2)
	v_pk_add_f32 v[236:237], v[236:237], v[248:249]
	s_waitcnt lgkmcnt(0)
	v_pk_add_f32 v[240:241], v[240:241], v[250:251]
	ds_bpermute_b32 v244, v174, v232
	ds_bpermute_b32 v245, v174, v233
	ds_bpermute_b32 v246, v174, v234
	ds_bpermute_b32 v247, v174, v235
	ds_bpermute_b32 v248, v174, v236
	ds_bpermute_b32 v249, v174, v237
	ds_bpermute_b32 v250, v174, v240
	ds_bpermute_b32 v251, v174, v241
	s_waitcnt lgkmcnt(6)
	v_pk_add_f32 v[232:233], v[232:233], v[244:245]
	s_waitcnt lgkmcnt(4)
	v_pk_add_f32 v[234:235], v[234:235], v[246:247]
	s_waitcnt lgkmcnt(2)
	v_pk_add_f32 v[236:237], v[236:237], v[248:249]
	s_waitcnt lgkmcnt(0)
	v_pk_add_f32 v[240:241], v[240:241], v[250:251]
	v_mul_f32_e32 v232, 0x3c800000, v232
	v_mul_f32_e32 v233, 0x3c800000, v233
	v_mul_f32_e32 v234, 0x3c800000, v234
	v_mul_f32_e32 v235, 0x3c800000, v235
	v_mul_f32_e32 v236, 0x3c800000, v236
	v_mul_f32_e32 v237, 0x3c800000, v237
	v_mul_f32_e32 v240, 0x3c800000, v240
	v_mul_f32_e32 v241, 0x3c800000, v241
	v_add_f32_e32 v232, 0x358637bd, v232
	v_add_f32_e32 v233, 0x358637bd, v233
	v_add_f32_e32 v234, 0x358637bd, v234
	v_add_f32_e32 v235, 0x358637bd, v235
	v_add_f32_e32 v236, 0x358637bd, v236
	v_add_f32_e32 v237, 0x358637bd, v237
	v_add_f32_e32 v240, 0x358637bd, v240
	v_add_f32_e32 v241, 0x358637bd, v241
	v_rsq_f32_e32 v232, v232
	v_rsq_f32_e32 v233, v233
	v_rsq_f32_e32 v234, v234
	v_rsq_f32_e32 v235, v235
	v_rsq_f32_e32 v236, v236
	v_rsq_f32_e32 v237, v237
	v_rsq_f32_e32 v240, v240
	v_rsq_f32_e32 v241, v241
	v_mul_f32_e32 v232, s9, v232
	v_mul_f32_e32 v233, s9, v233
	v_mul_f32_e32 v234, s9, v234
	v_mul_f32_e32 v235, s9, v235
	v_mul_f32_e32 v236, s9, v236
	v_mul_f32_e32 v237, s9, v237
	v_mul_f32_e32 v240, s9, v240
	v_mul_f32_e32 v241, s9, v241
	s_waitcnt vmcnt(12)
	v_pk_mul_f32 v[244:245], v[128:129], v[232:233] op_sel_hi:[1,0]
	v_pk_mul_f32 v[246:247], v[130:131], v[232:233] op_sel_hi:[1,0]
	v_pk_mul_f32 v[124:125], v[124:125], v[244:245]
	v_pk_mul_f32 v[126:127], v[126:127], v[246:247]
	v_pk_mul_f32 v[248:249], v[132:133], v[232:233] op_sel_hi:[1,0]
	v_pk_mul_f32 v[250:251], v[134:135], v[232:233] op_sel_hi:[1,0]
	s_waitcnt vmcnt(8)
	v_pk_mul_f32 v[172:173], v[184:185], v[124:125] op_sel:[1,1] op_sel_hi:[0,1]
	v_pk_mul_f32 v[174:175], v[186:187], v[126:127] op_sel:[1,1] op_sel_hi:[0,1]
	s_nop 0
	v_pk_fma_f32 v[124:125], v[184:185], v[124:125], v[172:173] op_sel_hi:[1,0,1] neg_lo:[0,0,1]
	v_pk_fma_f32 v[126:127], v[186:187], v[126:127], v[174:175] op_sel_hi:[1,0,1] neg_lo:[0,0,1]
	v_pk_mul_f32 v[120:121], v[120:121], v[248:249]
	v_pk_mul_f32 v[122:123], v[122:123], v[250:251]
	v_pk_mul_f32 v[244:245], v[136:137], v[232:233] op_sel_hi:[1,0]
	v_pk_mul_f32 v[246:247], v[138:139], v[232:233] op_sel_hi:[1,0]
	v_pk_mul_f32 v[172:173], v[188:189], v[120:121] op_sel:[1,1] op_sel_hi:[0,1]
	v_pk_mul_f32 v[174:175], v[190:191], v[122:123] op_sel:[1,1] op_sel_hi:[0,1]
	v_cvt_pk_bf16_f32 v124, v124, v125
	v_cvt_pk_bf16_f32 v125, v126, v127
	v_pk_fma_f32 v[120:121], v[188:189], v[120:121], v[172:173] op_sel_hi:[1,0,1] neg_lo:[0,0,1]
	v_pk_fma_f32 v[122:123], v[190:191], v[122:123], v[174:175] op_sel_hi:[1,0,1] neg_lo:[0,0,1]
	v_pk_mul_f32 v[92:93], v[92:93], v[244:245]
	v_pk_mul_f32 v[94:95], v[94:95], v[246:247]
	v_pk_mul_f32 v[248:249], v[140:141], v[232:233] op_sel_hi:[1,0]
	v_pk_mul_f32 v[250:251], v[142:143], v[232:233] op_sel_hi:[1,0]
	v_pk_mul_f32 v[172:173], v[192:193], v[92:93] op_sel:[1,1] op_sel_hi:[0,1]
	v_pk_mul_f32 v[174:175], v[194:195], v[94:95] op_sel:[1,1] op_sel_hi:[0,1]
	v_cvt_pk_bf16_f32 v126, v120, v121
	v_cvt_pk_bf16_f32 v127, v122, v123
	v_pk_fma_f32 v[92:93], v[192:193], v[92:93], v[172:173] op_sel_hi:[1,0,1] neg_lo:[0,0,1]
	v_pk_fma_f32 v[94:95], v[194:195], v[94:95], v[174:175] op_sel_hi:[1,0,1] neg_lo:[0,0,1]
	v_pk_mul_f32 v[88:89], v[88:89], v[248:249]
	v_pk_mul_f32 v[90:91], v[90:91], v[250:251]
	v_pk_mul_f32 v[244:245], v[128:129], v[232:233] op_sel:[0,1] op_sel_hi:[1,1]
	v_pk_mul_f32 v[246:247], v[130:131], v[232:233] op_sel:[0,1] op_sel_hi:[1,1]
	v_pk_mul_f32 v[172:173], v[196:197], v[88:89] op_sel:[1,1] op_sel_hi:[0,1]
	v_pk_mul_f32 v[174:175], v[198:199], v[90:91] op_sel:[1,1] op_sel_hi:[0,1]
	v_cvt_pk_bf16_f32 v92, v92, v93
	v_cvt_pk_bf16_f32 v93, v94, v95
	v_pk_fma_f32 v[88:89], v[196:197], v[88:89], v[172:173] op_sel_hi:[1,0,1] neg_lo:[0,0,1]
	v_pk_fma_f32 v[90:91], v[198:199], v[90:91], v[174:175] op_sel_hi:[1,0,1] neg_lo:[0,0,1]
	v_pk_mul_f32 v[116:117], v[116:117], v[244:245]
	v_pk_mul_f32 v[118:119], v[118:119], v[246:247]
	v_pk_mul_f32 v[248:249], v[132:133], v[232:233] op_sel:[0,1] op_sel_hi:[1,1]
	v_pk_mul_f32 v[250:251], v[134:135], v[232:233] op_sel:[0,1] op_sel_hi:[1,1]
	s_waitcnt vmcnt(4)
	v_pk_mul_f32 v[172:173], v[200:201], v[116:117] op_sel:[1,1] op_sel_hi:[0,1]
	v_pk_mul_f32 v[174:175], v[202:203], v[118:119] op_sel:[1,1] op_sel_hi:[0,1]
	v_cvt_pk_bf16_f32 v94, v88, v89
	v_cvt_pk_bf16_f32 v95, v90, v91
	global_load_dwordx4 v[188:191], v177, s[42:43] offset:16
	global_load_dwordx4 v[196:199], v177, s[42:43] offset:144
	global_load_dwordx4 v[184:187], v177, s[42:43]
	global_load_dwordx4 v[192:195], v177, s[42:43] offset:128
	s_add_u32 s42, s42, 0x5000
	s_addc_u32 s43, s43, 0
	v_pk_fma_f32 v[116:117], v[200:201], v[116:117], v[172:173] op_sel_hi:[1,0,1] neg_lo:[0,0,1]
	v_pk_fma_f32 v[118:119], v[202:203], v[118:119], v[174:175] op_sel_hi:[1,0,1] neg_lo:[0,0,1]
	v_pk_mul_f32 v[112:113], v[112:113], v[248:249]
	v_pk_mul_f32 v[114:115], v[114:115], v[250:251]
	v_pk_mul_f32 v[244:245], v[136:137], v[232:233] op_sel:[0,1] op_sel_hi:[1,1]
	v_pk_mul_f32 v[246:247], v[138:139], v[232:233] op_sel:[0,1] op_sel_hi:[1,1]
	v_pk_mul_f32 v[172:173], v[204:205], v[112:113] op_sel:[1,1] op_sel_hi:[0,1]
	v_pk_mul_f32 v[174:175], v[206:207], v[114:115] op_sel:[1,1] op_sel_hi:[0,1]
	v_cvt_pk_bf16_f32 v116, v116, v117
	v_cvt_pk_bf16_f32 v117, v118, v119
	v_pk_fma_f32 v[112:113], v[204:205], v[112:113], v[172:173] op_sel_hi:[1,0,1] neg_lo:[0,0,1]
	v_pk_fma_f32 v[114:115], v[206:207], v[114:115], v[174:175] op_sel_hi:[1,0,1] neg_lo:[0,0,1]
	v_pk_mul_f32 v[84:85], v[84:85], v[244:245]
	v_pk_mul_f32 v[86:87], v[86:87], v[246:247]
	v_pk_mul_f32 v[248:249], v[140:141], v[232:233] op_sel:[0,1] op_sel_hi:[1,1]
	v_pk_mul_f32 v[250:251], v[142:143], v[232:233] op_sel:[0,1] op_sel_hi:[1,1]
	v_pk_mul_f32 v[172:173], v[208:209], v[84:85] op_sel:[1,1] op_sel_hi:[0,1]
	v_pk_mul_f32 v[174:175], v[210:211], v[86:87] op_sel:[1,1] op_sel_hi:[0,1]
	v_cvt_pk_bf16_f32 v118, v112, v113
	v_cvt_pk_bf16_f32 v119, v114, v115
	v_pk_fma_f32 v[84:85], v[208:209], v[84:85], v[172:173] op_sel_hi:[1,0,1] neg_lo:[0,0,1]
	v_pk_fma_f32 v[86:87], v[210:211], v[86:87], v[174:175] op_sel_hi:[1,0,1] neg_lo:[0,0,1]
	v_pk_mul_f32 v[80:81], v[80:81], v[248:249]
	v_pk_mul_f32 v[82:83], v[82:83], v[250:251]
	v_pk_mul_f32 v[244:245], v[128:129], v[234:235] op_sel_hi:[1,0]
	v_pk_mul_f32 v[246:247], v[130:131], v[234:235] op_sel_hi:[1,0]
	v_pk_mul_f32 v[172:173], v[212:213], v[80:81] op_sel:[1,1] op_sel_hi:[0,1]
	v_pk_mul_f32 v[174:175], v[214:215], v[82:83] op_sel:[1,1] op_sel_hi:[0,1]
	v_cvt_pk_bf16_f32 v84, v84, v85
	v_cvt_pk_bf16_f32 v85, v86, v87
	v_pk_fma_f32 v[80:81], v[212:213], v[80:81], v[172:173] op_sel_hi:[1,0,1] neg_lo:[0,0,1]
	v_pk_fma_f32 v[82:83], v[214:215], v[82:83], v[174:175] op_sel_hi:[1,0,1] neg_lo:[0,0,1]
	v_pk_mul_f32 v[108:109], v[108:109], v[244:245]
	v_pk_mul_f32 v[110:111], v[110:111], v[246:247]
	v_pk_mul_f32 v[248:249], v[132:133], v[234:235] op_sel_hi:[1,0]
	v_pk_mul_f32 v[250:251], v[134:135], v[234:235] op_sel_hi:[1,0]
	s_waitcnt vmcnt(4)
	v_pk_mul_f32 v[172:173], v[216:217], v[108:109] op_sel:[1,1] op_sel_hi:[0,1]
	v_pk_mul_f32 v[174:175], v[218:219], v[110:111] op_sel:[1,1] op_sel_hi:[0,1]
	v_cvt_pk_bf16_f32 v86, v80, v81
	v_cvt_pk_bf16_f32 v87, v82, v83
	global_load_dwordx4 v[204:207], v177, s[42:43] offset:16
	global_load_dwordx4 v[212:215], v177, s[42:43] offset:144
	global_load_dwordx4 v[200:203], v177, s[42:43]
	global_load_dwordx4 v[208:211], v177, s[42:43] offset:128
	s_add_u32 s42, s42, 0x1000
	s_addc_u32 s43, s43, 0
	v_pk_fma_f32 v[108:109], v[216:217], v[108:109], v[172:173] op_sel_hi:[1,0,1] neg_lo:[0,0,1]
	v_pk_fma_f32 v[110:111], v[218:219], v[110:111], v[174:175] op_sel_hi:[1,0,1] neg_lo:[0,0,1]
	v_pk_mul_f32 v[104:105], v[104:105], v[248:249]
	v_pk_mul_f32 v[106:107], v[106:107], v[250:251]
	v_pk_mul_f32 v[244:245], v[136:137], v[234:235] op_sel_hi:[1,0]
	v_pk_mul_f32 v[246:247], v[138:139], v[234:235] op_sel_hi:[1,0]
	v_pk_mul_f32 v[172:173], v[220:221], v[104:105] op_sel:[1,1] op_sel_hi:[0,1]
	v_pk_mul_f32 v[174:175], v[222:223], v[106:107] op_sel:[1,1] op_sel_hi:[0,1]
	v_cvt_pk_bf16_f32 v108, v108, v109
	v_cvt_pk_bf16_f32 v109, v110, v111
	v_pk_fma_f32 v[104:105], v[220:221], v[104:105], v[172:173] op_sel_hi:[1,0,1] neg_lo:[0,0,1]
	v_pk_fma_f32 v[106:107], v[222:223], v[106:107], v[174:175] op_sel_hi:[1,0,1] neg_lo:[0,0,1]
	v_pk_mul_f32 v[76:77], v[76:77], v[244:245]
	v_pk_mul_f32 v[78:79], v[78:79], v[246:247]
	v_pk_mul_f32 v[248:249], v[140:141], v[234:235] op_sel_hi:[1,0]
	v_pk_mul_f32 v[250:251], v[142:143], v[234:235] op_sel_hi:[1,0]
	v_pk_mul_f32 v[172:173], v[164:165], v[76:77] op_sel:[1,1] op_sel_hi:[0,1]
	v_pk_mul_f32 v[174:175], v[166:167], v[78:79] op_sel:[1,1] op_sel_hi:[0,1]
	v_cvt_pk_bf16_f32 v110, v104, v105
	v_cvt_pk_bf16_f32 v111, v106, v107
	v_pk_fma_f32 v[76:77], v[164:165], v[76:77], v[172:173] op_sel_hi:[1,0,1] neg_lo:[0,0,1]
	v_pk_fma_f32 v[78:79], v[166:167], v[78:79], v[174:175] op_sel_hi:[1,0,1] neg_lo:[0,0,1]
	v_pk_mul_f32 v[72:73], v[72:73], v[248:249]
	v_pk_mul_f32 v[74:75], v[74:75], v[250:251]
	v_pk_mul_f32 v[244:245], v[128:129], v[234:235] op_sel:[0,1] op_sel_hi:[1,1]
	v_pk_mul_f32 v[246:247], v[130:131], v[234:235] op_sel:[0,1] op_sel_hi:[1,1]
	v_pk_mul_f32 v[172:173], v[168:169], v[72:73] op_sel:[1,1] op_sel_hi:[0,1]
	v_pk_mul_f32 v[174:175], v[170:171], v[74:75] op_sel:[1,1] op_sel_hi:[0,1]
	v_cvt_pk_bf16_f32 v76, v76, v77
	v_cvt_pk_bf16_f32 v77, v78, v79
	v_pk_fma_f32 v[72:73], v[168:169], v[72:73], v[172:173] op_sel_hi:[1,0,1] neg_lo:[0,0,1]
	v_pk_fma_f32 v[74:75], v[170:171], v[74:75], v[174:175] op_sel_hi:[1,0,1] neg_lo:[0,0,1]
	v_pk_mul_f32 v[100:101], v[100:101], v[244:245]
	v_pk_mul_f32 v[102:103], v[102:103], v[246:247]
	v_pk_mul_f32 v[248:249], v[132:133], v[234:235] op_sel:[0,1] op_sel_hi:[1,1]
	v_pk_mul_f32 v[250:251], v[134:135], v[234:235] op_sel:[0,1] op_sel_hi:[1,1]
	s_waitcnt vmcnt(4)
	v_pk_mul_f32 v[172:173], v[184:185], v[100:101] op_sel:[1,1] op_sel_hi:[0,1]
	v_pk_mul_f32 v[174:175], v[186:187], v[102:103] op_sel:[1,1] op_sel_hi:[0,1]
	v_cvt_pk_bf16_f32 v78, v72, v73
	v_cvt_pk_bf16_f32 v79, v74, v75
	global_load_dwordx4 v[220:223], v177, s[42:43] offset:16
	global_load_dwordx4 v[168:171], v177, s[42:43] offset:144
	global_load_dwordx4 v[216:219], v177, s[42:43]
	global_load_dwordx4 v[164:167], v177, s[42:43] offset:128
	s_add_u32 s42, s42, 0x1000
	s_addc_u32 s43, s43, 0
	v_pk_fma_f32 v[100:101], v[184:185], v[100:101], v[172:173] op_sel_hi:[1,0,1] neg_lo:[0,0,1]
	v_pk_fma_f32 v[102:103], v[186:187], v[102:103], v[174:175] op_sel_hi:[1,0,1] neg_lo:[0,0,1]
	v_pk_mul_f32 v[96:97], v[96:97], v[248:249]
	v_pk_mul_f32 v[98:99], v[98:99], v[250:251]
	v_pk_mul_f32 v[244:245], v[136:137], v[234:235] op_sel:[0,1] op_sel_hi:[1,1]
	v_pk_mul_f32 v[246:247], v[138:139], v[234:235] op_sel:[0,1] op_sel_hi:[1,1]
	v_pk_mul_f32 v[172:173], v[188:189], v[96:97] op_sel:[1,1] op_sel_hi:[0,1]
	v_pk_mul_f32 v[174:175], v[190:191], v[98:99] op_sel:[1,1] op_sel_hi:[0,1]
	v_cvt_pk_bf16_f32 v100, v100, v101
	v_cvt_pk_bf16_f32 v101, v102, v103
	v_pk_fma_f32 v[96:97], v[188:189], v[96:97], v[172:173] op_sel_hi:[1,0,1] neg_lo:[0,0,1]
	v_pk_fma_f32 v[98:99], v[190:191], v[98:99], v[174:175] op_sel_hi:[1,0,1] neg_lo:[0,0,1]
	v_pk_mul_f32 v[68:69], v[68:69], v[244:245]
	v_pk_mul_f32 v[70:71], v[70:71], v[246:247]
	v_pk_mul_f32 v[248:249], v[140:141], v[234:235] op_sel:[0,1] op_sel_hi:[1,1]
	v_pk_mul_f32 v[250:251], v[142:143], v[234:235] op_sel:[0,1] op_sel_hi:[1,1]
	v_pk_mul_f32 v[172:173], v[192:193], v[68:69] op_sel:[1,1] op_sel_hi:[0,1]
	v_pk_mul_f32 v[174:175], v[194:195], v[70:71] op_sel:[1,1] op_sel_hi:[0,1]
	v_cvt_pk_bf16_f32 v102, v96, v97
	v_cvt_pk_bf16_f32 v103, v98, v99
	v_pk_fma_f32 v[68:69], v[192:193], v[68:69], v[172:173] op_sel_hi:[1,0,1] neg_lo:[0,0,1]
	v_pk_fma_f32 v[70:71], v[194:195], v[70:71], v[174:175] op_sel_hi:[1,0,1] neg_lo:[0,0,1]
	v_pk_mul_f32 v[64:65], v[64:65], v[248:249]
	v_pk_mul_f32 v[66:67], v[66:67], v[250:251]
	v_pk_mul_f32 v[244:245], v[128:129], v[236:237] op_sel_hi:[1,0]
	v_pk_mul_f32 v[246:247], v[130:131], v[236:237] op_sel_hi:[1,0]
	v_pk_mul_f32 v[172:173], v[196:197], v[64:65] op_sel:[1,1] op_sel_hi:[0,1]
	v_pk_mul_f32 v[174:175], v[198:199], v[66:67] op_sel:[1,1] op_sel_hi:[0,1]
	v_cvt_pk_bf16_f32 v68, v68, v69
	v_cvt_pk_bf16_f32 v69, v70, v71
	v_pk_fma_f32 v[64:65], v[196:197], v[64:65], v[172:173] op_sel_hi:[1,0,1] neg_lo:[0,0,1]
	v_pk_fma_f32 v[66:67], v[198:199], v[66:67], v[174:175] op_sel_hi:[1,0,1] neg_lo:[0,0,1]
	v_pk_mul_f32 v[60:61], v[60:61], v[244:245]
	v_pk_mul_f32 v[62:63], v[62:63], v[246:247]
	v_pk_mul_f32 v[248:249], v[132:133], v[236:237] op_sel_hi:[1,0]
	v_pk_mul_f32 v[250:251], v[134:135], v[236:237] op_sel_hi:[1,0]
	s_waitcnt vmcnt(4)
	v_pk_mul_f32 v[172:173], v[200:201], v[60:61] op_sel:[1,1] op_sel_hi:[0,1]
	v_pk_mul_f32 v[174:175], v[202:203], v[62:63] op_sel:[1,1] op_sel_hi:[0,1]
	v_cvt_pk_bf16_f32 v70, v64, v65
	v_cvt_pk_bf16_f32 v71, v66, v67
	global_load_dwordx4 v[188:191], v177, s[42:43] offset:16
	global_load_dwordx4 v[196:199], v177, s[42:43] offset:144
	global_load_dwordx4 v[184:187], v177, s[42:43]
	global_load_dwordx4 v[192:195], v177, s[42:43] offset:128
	s_add_u32 s42, s42, 0x1000
	s_addc_u32 s43, s43, 0
	v_pk_fma_f32 v[60:61], v[200:201], v[60:61], v[172:173] op_sel_hi:[1,0,1] neg_lo:[0,0,1]
	v_pk_fma_f32 v[62:63], v[202:203], v[62:63], v[174:175] op_sel_hi:[1,0,1] neg_lo:[0,0,1]
	v_pk_mul_f32 v[56:57], v[56:57], v[248:249]
	v_pk_mul_f32 v[58:59], v[58:59], v[250:251]
	v_pk_mul_f32 v[244:245], v[136:137], v[236:237] op_sel_hi:[1,0]
	v_pk_mul_f32 v[246:247], v[138:139], v[236:237] op_sel_hi:[1,0]
	v_pk_mul_f32 v[172:173], v[204:205], v[56:57] op_sel:[1,1] op_sel_hi:[0,1]
	v_pk_mul_f32 v[174:175], v[206:207], v[58:59] op_sel:[1,1] op_sel_hi:[0,1]
	v_cvt_pk_bf16_f32 v60, v60, v61
	v_cvt_pk_bf16_f32 v61, v62, v63
	v_pk_fma_f32 v[56:57], v[204:205], v[56:57], v[172:173] op_sel_hi:[1,0,1] neg_lo:[0,0,1]
	v_pk_fma_f32 v[58:59], v[206:207], v[58:59], v[174:175] op_sel_hi:[1,0,1] neg_lo:[0,0,1]
	v_pk_mul_f32 v[28:29], v[28:29], v[244:245]
	v_pk_mul_f32 v[30:31], v[30:31], v[246:247]
	v_pk_mul_f32 v[248:249], v[140:141], v[236:237] op_sel_hi:[1,0]
	v_pk_mul_f32 v[250:251], v[142:143], v[236:237] op_sel_hi:[1,0]
	v_pk_mul_f32 v[172:173], v[208:209], v[28:29] op_sel:[1,1] op_sel_hi:[0,1]
	v_pk_mul_f32 v[174:175], v[210:211], v[30:31] op_sel:[1,1] op_sel_hi:[0,1]
	v_cvt_pk_bf16_f32 v62, v56, v57
	v_cvt_pk_bf16_f32 v63, v58, v59
	v_pk_fma_f32 v[28:29], v[208:209], v[28:29], v[172:173] op_sel_hi:[1,0,1] neg_lo:[0,0,1]
	v_pk_fma_f32 v[30:31], v[210:211], v[30:31], v[174:175] op_sel_hi:[1,0,1] neg_lo:[0,0,1]
	v_pk_mul_f32 v[24:25], v[24:25], v[248:249]
	v_pk_mul_f32 v[26:27], v[26:27], v[250:251]
	v_pk_mul_f32 v[244:245], v[128:129], v[236:237] op_sel:[0,1] op_sel_hi:[1,1]
	v_pk_mul_f32 v[246:247], v[130:131], v[236:237] op_sel:[0,1] op_sel_hi:[1,1]
	v_pk_mul_f32 v[172:173], v[212:213], v[24:25] op_sel:[1,1] op_sel_hi:[0,1]
	v_pk_mul_f32 v[174:175], v[214:215], v[26:27] op_sel:[1,1] op_sel_hi:[0,1]
	v_cvt_pk_bf16_f32 v28, v28, v29
	v_cvt_pk_bf16_f32 v29, v30, v31
	v_pk_fma_f32 v[24:25], v[212:213], v[24:25], v[172:173] op_sel_hi:[1,0,1] neg_lo:[0,0,1]
	v_pk_fma_f32 v[26:27], v[214:215], v[26:27], v[174:175] op_sel_hi:[1,0,1] neg_lo:[0,0,1]
	v_pk_mul_f32 v[52:53], v[52:53], v[244:245]
	v_pk_mul_f32 v[54:55], v[54:55], v[246:247]
	v_pk_mul_f32 v[248:249], v[132:133], v[236:237] op_sel:[0,1] op_sel_hi:[1,1]
	v_pk_mul_f32 v[250:251], v[134:135], v[236:237] op_sel:[0,1] op_sel_hi:[1,1]
	s_waitcnt vmcnt(4)
	v_pk_mul_f32 v[172:173], v[216:217], v[52:53] op_sel:[1,1] op_sel_hi:[0,1]
	v_pk_mul_f32 v[174:175], v[218:219], v[54:55] op_sel:[1,1] op_sel_hi:[0,1]
	v_cvt_pk_bf16_f32 v30, v24, v25
	v_cvt_pk_bf16_f32 v31, v26, v27
	global_load_dwordx4 v[204:207], v177, s[42:43] offset:16
	global_load_dwordx4 v[212:215], v177, s[42:43] offset:144
	global_load_dwordx4 v[200:203], v177, s[42:43]
	global_load_dwordx4 v[208:211], v177, s[42:43] offset:128
	global_store_dwordx4 v176, v[124:127], s[44:45]
	global_store_dwordx4 v176, v[92:95], s[44:45] offset:64
	s_add_u32 s44, s44, s24
	s_addc_u32 s45, s45, 0
	global_store_dwordx4 v176, v[116:119], s[44:45]
	global_store_dwordx4 v176, v[84:87], s[44:45] offset:64
	s_add_u32 s44, s44, s24
	s_addc_u32 s45, s45, 0
	global_store_dwordx4 v176, v[108:111], s[44:45]
	global_store_dwordx4 v176, v[76:79], s[44:45] offset:64
	s_add_u32 s44, s44, s24
	s_addc_u32 s45, s45, 0
	global_store_dwordx4 v176, v[100:103], s[44:45]
	global_store_dwordx4 v176, v[68:71], s[44:45] offset:64
	s_lshl_b32 s2, 0x50, s8
	s_add_u32 s44, s44, s2
	s_addc_u32 s45, s45, 0
	global_store_dwordx4 v176, v[60:63], s[44:45]
	global_store_dwordx4 v176, v[28:31], s[44:45] offset:64
	v_pk_fma_f32 v[52:53], v[216:217], v[52:53], v[172:173] op_sel_hi:[1,0,1] neg_lo:[0,0,1]
	v_pk_fma_f32 v[54:55], v[218:219], v[54:55], v[174:175] op_sel_hi:[1,0,1] neg_lo:[0,0,1]
	v_pk_mul_f32 v[48:49], v[48:49], v[248:249]
	v_pk_mul_f32 v[50:51], v[50:51], v[250:251]
	v_pk_mul_f32 v[244:245], v[136:137], v[236:237] op_sel:[0,1] op_sel_hi:[1,1]
	v_pk_mul_f32 v[246:247], v[138:139], v[236:237] op_sel:[0,1] op_sel_hi:[1,1]
	v_pk_mul_f32 v[172:173], v[220:221], v[48:49] op_sel:[1,1] op_sel_hi:[0,1]
	v_pk_mul_f32 v[174:175], v[222:223], v[50:51] op_sel:[1,1] op_sel_hi:[0,1]
	v_cvt_pk_bf16_f32 v52, v52, v53
	v_cvt_pk_bf16_f32 v53, v54, v55
	v_pk_fma_f32 v[48:49], v[220:221], v[48:49], v[172:173] op_sel_hi:[1,0,1] neg_lo:[0,0,1]
	v_pk_fma_f32 v[50:51], v[222:223], v[50:51], v[174:175] op_sel_hi:[1,0,1] neg_lo:[0,0,1]
	v_pk_mul_f32 v[20:21], v[20:21], v[244:245]
	v_pk_mul_f32 v[22:23], v[22:23], v[246:247]
	v_pk_mul_f32 v[248:249], v[140:141], v[236:237] op_sel:[0,1] op_sel_hi:[1,1]
	v_pk_mul_f32 v[250:251], v[142:143], v[236:237] op_sel:[0,1] op_sel_hi:[1,1]
	v_pk_mul_f32 v[172:173], v[164:165], v[20:21] op_sel:[1,1] op_sel_hi:[0,1]
	v_pk_mul_f32 v[174:175], v[166:167], v[22:23] op_sel:[1,1] op_sel_hi:[0,1]
	v_cvt_pk_bf16_f32 v54, v48, v49
	v_cvt_pk_bf16_f32 v55, v50, v51
	v_pk_fma_f32 v[20:21], v[164:165], v[20:21], v[172:173] op_sel_hi:[1,0,1] neg_lo:[0,0,1]
	v_pk_fma_f32 v[22:23], v[166:167], v[22:23], v[174:175] op_sel_hi:[1,0,1] neg_lo:[0,0,1]
	v_pk_mul_f32 v[16:17], v[16:17], v[248:249]
	v_pk_mul_f32 v[18:19], v[18:19], v[250:251]
	v_pk_mul_f32 v[244:245], v[128:129], v[240:241] op_sel_hi:[1,0]
	v_pk_mul_f32 v[246:247], v[130:131], v[240:241] op_sel_hi:[1,0]
	v_pk_mul_f32 v[172:173], v[168:169], v[16:17] op_sel:[1,1] op_sel_hi:[0,1]
	v_pk_mul_f32 v[174:175], v[170:171], v[18:19] op_sel:[1,1] op_sel_hi:[0,1]
	v_cvt_pk_bf16_f32 v20, v20, v21
	v_cvt_pk_bf16_f32 v21, v22, v23
	v_pk_fma_f32 v[16:17], v[168:169], v[16:17], v[172:173] op_sel_hi:[1,0,1] neg_lo:[0,0,1]
	v_pk_fma_f32 v[18:19], v[170:171], v[18:19], v[174:175] op_sel_hi:[1,0,1] neg_lo:[0,0,1]
	v_pk_mul_f32 v[44:45], v[44:45], v[244:245]
	v_pk_mul_f32 v[46:47], v[46:47], v[246:247]
	v_pk_mul_f32 v[248:249], v[132:133], v[240:241] op_sel_hi:[1,0]
	v_pk_mul_f32 v[250:251], v[134:135], v[240:241] op_sel_hi:[1,0]
	s_waitcnt vmcnt(14)
	v_pk_mul_f32 v[172:173], v[184:185], v[44:45] op_sel:[1,1] op_sel_hi:[0,1]
	v_pk_mul_f32 v[174:175], v[186:187], v[46:47] op_sel:[1,1] op_sel_hi:[0,1]
	v_cvt_pk_bf16_f32 v22, v16, v17
	v_cvt_pk_bf16_f32 v23, v18, v19
	s_add_u32 s44, s44, s24
	s_addc_u32 s45, s45, 0
	global_store_dwordx4 v176, v[52:55], s[44:45]
	global_store_dwordx4 v176, v[20:23], s[44:45] offset:64
	v_pk_fma_f32 v[44:45], v[184:185], v[44:45], v[172:173] op_sel_hi:[1,0,1] neg_lo:[0,0,1]
	v_pk_fma_f32 v[46:47], v[186:187], v[46:47], v[174:175] op_sel_hi:[1,0,1] neg_lo:[0,0,1]
	v_pk_mul_f32 v[40:41], v[40:41], v[248:249]
	v_pk_mul_f32 v[42:43], v[42:43], v[250:251]
	v_pk_mul_f32 v[244:245], v[136:137], v[240:241] op_sel_hi:[1,0]
	v_pk_mul_f32 v[246:247], v[138:139], v[240:241] op_sel_hi:[1,0]
	v_pk_mul_f32 v[172:173], v[188:189], v[40:41] op_sel:[1,1] op_sel_hi:[0,1]
	v_pk_mul_f32 v[174:175], v[190:191], v[42:43] op_sel:[1,1] op_sel_hi:[0,1]
	v_cvt_pk_bf16_f32 v44, v44, v45
	v_cvt_pk_bf16_f32 v45, v46, v47
	v_pk_fma_f32 v[40:41], v[188:189], v[40:41], v[172:173] op_sel_hi:[1,0,1] neg_lo:[0,0,1]
	v_pk_fma_f32 v[42:43], v[190:191], v[42:43], v[174:175] op_sel_hi:[1,0,1] neg_lo:[0,0,1]
	v_pk_mul_f32 v[12:13], v[12:13], v[244:245]
	v_pk_mul_f32 v[14:15], v[14:15], v[246:247]
	v_pk_mul_f32 v[248:249], v[140:141], v[240:241] op_sel_hi:[1,0]
	v_pk_mul_f32 v[250:251], v[142:143], v[240:241] op_sel_hi:[1,0]
	v_pk_mul_f32 v[172:173], v[192:193], v[12:13] op_sel:[1,1] op_sel_hi:[0,1]
	v_pk_mul_f32 v[174:175], v[194:195], v[14:15] op_sel:[1,1] op_sel_hi:[0,1]
	v_cvt_pk_bf16_f32 v46, v40, v41
	v_cvt_pk_bf16_f32 v47, v42, v43
	v_pk_fma_f32 v[12:13], v[192:193], v[12:13], v[172:173] op_sel_hi:[1,0,1] neg_lo:[0,0,1]
	v_pk_fma_f32 v[14:15], v[194:195], v[14:15], v[174:175] op_sel_hi:[1,0,1] neg_lo:[0,0,1]
	v_pk_mul_f32 v[8:9], v[8:9], v[248:249]
	v_pk_mul_f32 v[10:11], v[10:11], v[250:251]
	v_pk_mul_f32 v[244:245], v[128:129], v[240:241] op_sel:[0,1] op_sel_hi:[1,1]
	v_pk_mul_f32 v[246:247], v[130:131], v[240:241] op_sel:[0,1] op_sel_hi:[1,1]
	v_pk_mul_f32 v[172:173], v[196:197], v[8:9] op_sel:[1,1] op_sel_hi:[0,1]
	v_pk_mul_f32 v[174:175], v[198:199], v[10:11] op_sel:[1,1] op_sel_hi:[0,1]
	v_cvt_pk_bf16_f32 v12, v12, v13
	v_cvt_pk_bf16_f32 v13, v14, v15
	v_pk_fma_f32 v[8:9], v[196:197], v[8:9], v[172:173] op_sel_hi:[1,0,1] neg_lo:[0,0,1]
	v_pk_fma_f32 v[10:11], v[198:199], v[10:11], v[174:175] op_sel_hi:[1,0,1] neg_lo:[0,0,1]
	v_pk_mul_f32 v[36:37], v[36:37], v[244:245]
	v_pk_mul_f32 v[38:39], v[38:39], v[246:247]
	v_pk_mul_f32 v[248:249], v[132:133], v[240:241] op_sel:[0,1] op_sel_hi:[1,1]
	v_pk_mul_f32 v[250:251], v[134:135], v[240:241] op_sel:[0,1] op_sel_hi:[1,1]
	s_waitcnt vmcnt(12)
	v_pk_mul_f32 v[172:173], v[200:201], v[36:37] op_sel:[1,1] op_sel_hi:[0,1]
	v_pk_mul_f32 v[174:175], v[202:203], v[38:39] op_sel:[1,1] op_sel_hi:[0,1]
	v_cvt_pk_bf16_f32 v14, v8, v9
	v_cvt_pk_bf16_f32 v15, v10, v11
	s_add_u32 s44, s44, s24
	s_addc_u32 s45, s45, 0
	global_store_dwordx4 v176, v[44:47], s[44:45]
	global_store_dwordx4 v176, v[12:15], s[44:45] offset:64
	v_pk_fma_f32 v[36:37], v[200:201], v[36:37], v[172:173] op_sel_hi:[1,0,1] neg_lo:[0,0,1]
	v_pk_fma_f32 v[38:39], v[202:203], v[38:39], v[174:175] op_sel_hi:[1,0,1] neg_lo:[0,0,1]
	v_pk_mul_f32 v[32:33], v[32:33], v[248:249]
	v_pk_mul_f32 v[34:35], v[34:35], v[250:251]
	v_pk_mul_f32 v[244:245], v[136:137], v[240:241] op_sel:[0,1] op_sel_hi:[1,1]
	v_pk_mul_f32 v[246:247], v[138:139], v[240:241] op_sel:[0,1] op_sel_hi:[1,1]
	v_pk_mul_f32 v[172:173], v[204:205], v[32:33] op_sel:[1,1] op_sel_hi:[0,1]
	v_pk_mul_f32 v[174:175], v[206:207], v[34:35] op_sel:[1,1] op_sel_hi:[0,1]
	v_cvt_pk_bf16_f32 v36, v36, v37
	v_cvt_pk_bf16_f32 v37, v38, v39
	v_pk_fma_f32 v[32:33], v[204:205], v[32:33], v[172:173] op_sel_hi:[1,0,1] neg_lo:[0,0,1]
	v_pk_fma_f32 v[34:35], v[206:207], v[34:35], v[174:175] op_sel_hi:[1,0,1] neg_lo:[0,0,1]
	v_pk_mul_f32 v[4:5], v[4:5], v[244:245]
	v_pk_mul_f32 v[6:7], v[6:7], v[246:247]
	v_pk_mul_f32 v[248:249], v[140:141], v[240:241] op_sel:[0,1] op_sel_hi:[1,1]
	v_pk_mul_f32 v[250:251], v[142:143], v[240:241] op_sel:[0,1] op_sel_hi:[1,1]
	v_pk_mul_f32 v[172:173], v[208:209], v[4:5] op_sel:[1,1] op_sel_hi:[0,1]
	v_pk_mul_f32 v[174:175], v[210:211], v[6:7] op_sel:[1,1] op_sel_hi:[0,1]
	v_cvt_pk_bf16_f32 v38, v32, v33
	v_cvt_pk_bf16_f32 v39, v34, v35
	v_pk_fma_f32 v[4:5], v[208:209], v[4:5], v[172:173] op_sel_hi:[1,0,1] neg_lo:[0,0,1]
	v_pk_fma_f32 v[6:7], v[210:211], v[6:7], v[174:175] op_sel_hi:[1,0,1] neg_lo:[0,0,1]
	v_pk_mul_f32 v[0:1], v[0:1], v[248:249]
	v_pk_mul_f32 v[2:3], v[2:3], v[250:251]
	v_pk_mul_f32 v[172:173], v[212:213], v[0:1] op_sel:[1,1] op_sel_hi:[0,1]
	v_pk_mul_f32 v[174:175], v[214:215], v[2:3] op_sel:[1,1] op_sel_hi:[0,1]
	v_cvt_pk_bf16_f32 v4, v4, v5
	v_cvt_pk_bf16_f32 v5, v6, v7
	v_pk_fma_f32 v[0:1], v[212:213], v[0:1], v[172:173] op_sel_hi:[1,0,1] neg_lo:[0,0,1]
	v_pk_fma_f32 v[2:3], v[214:215], v[2:3], v[174:175] op_sel_hi:[1,0,1] neg_lo:[0,0,1]
	s_nop 0
	v_cvt_pk_bf16_f32 v6, v0, v1
	v_cvt_pk_bf16_f32 v7, v2, v3
	s_add_u32 s44, s44, s24
	s_addc_u32 s45, s45, 0
	global_store_dwordx4 v176, v[36:39], s[44:45]
	global_store_dwordx4 v176, v[4:7], s[44:45] offset:64
